# attention softmax row-max as 16-op v_max3 chain (4 sites) on top of glds prologue, epiconv, spatial LDS, sc1
# speedup vs baseline: 1.0036x; 1.0036x over previous
.LBB0_931:
	s_lshl_b32 s34, s46, 7
	s_cmpk_gt_i32 s46, 0xff
	s_mov_b64 s[2:3], -1
	s_waitcnt vmcnt(4)
	v_lshlrev_b32_e32 v106, 1, v156
	v_add_u32_e32 v212, v203, v157
	s_cbranch_scc0 .LBB0_940
	s_lshl_b32 s2, s46, 4
	s_and_b32 s2, s2, 0x7fffff00
	s_bfe_u32 s35, s46, 0x30001
	s_add_i32 s10, s2, 0xfffff000
	v_add_u32_e32 v2, s10, v199
	s_mul_i32 s2, s35, 0x2800
	s_and_b32 s47, s34, 0x80
	v_add_u32_e32 v4, s2, v2
	s_mul_i32 s2, s35, 0x140000
	s_add_u32 s2, s33, s2
	v_mov_b32_e32 v3, v1
	v_mov_b32_e32 v5, v1
	s_addc_u32 s3, s36, 0
	v_lshlrev_b64 v[4:5], 7, v[4:5]
	v_lshlrev_b64 v[6:7], 6, v[2:3]
	v_lshl_add_u64 v[2:3], v[2:3], 1, s[2:3]
	v_lshl_add_u64 v[22:23], s[14:15], 0, v[4:5]
	v_lshl_add_u64 v[4:5], v[2:3], 0, v[150:151]
	v_lshl_add_u64 v[2:3], v[2:3], 0, v[152:153]
	v_mov_b32_e32 v175, v1
	v_lshl_add_u64 v[24:25], v[4:5], 0, v[174:175]
	v_lshl_add_u64 v[26:27], v[2:3], 0, v[174:175]
	v_lshl_add_u64 v[10:11], v[154:155], 0, v[6:7]
	v_mov_b32_e32 v177, v1
	v_lshl_add_u64 v[2:3], v[22:23], 0, v[158:159]
	v_lshl_add_u64 v[4:5], v[22:23], 0, v[160:161]
	v_lshl_add_u64 v[2:3], v[2:3], 0, v[174:175]
	v_lshl_add_u64 v[6:7], v[4:5], 0, v[174:175]
	v_lshl_add_u64 v[28:29], v[10:11], 0, v[176:177]
	global_load_dwordx4 v[2:5], v[2:3], off
	s_nop 0
	global_load_dwordx4 v[6:9], v[6:7], off
	s_nop 0
	global_load_dwordx4 v[10:13], v[28:29], off
	global_load_dwordx4 v[14:17], v[24:25], off
	global_load_dwordx4 v[18:21], v[26:27], off
	v_or_b32_e32 v0, s47, v198
	v_or_b32_e32 v0, s10, v0
	v_mov_b64_e32 v[30:31], s[12:13]
	v_mad_u64_u32 v[30:31], s[2:3], v0, s40, v[30:31]
	s_mul_i32 s10, s35, 0xc0
	v_lshl_add_u64 v[30:31], v[30:31], 0, s[10:11]
	v_mov_b32_e32 v149, v1
	v_lshl_add_u64 v[30:31], v[30:31], 0, v[148:149]
	global_load_dwordx4 v[82:85], v[30:31], off nt
	global_load_dwordx4 v[78:81], v[30:31], off offset:32 nt
	global_load_dwordx4 v[44:47], v[26:27], off offset:128
	global_load_dwordx4 v[66:69], v[30:31], off offset:64 nt
	global_load_dwordx4 v[48:51], v[24:25], off offset:128
	v_add_co_u32_e32 v24, vcc, s37, v28
	v_mov_b32_e32 v107, v1
	s_nop 0
	v_addc_co_u32_e32 v25, vcc, 0, v29, vcc
	global_load_dwordx4 v[52:55], v[24:25], off
	global_load_dwordx4 v[86:89], v[30:31], off offset:96 nt
	global_load_dwordx4 v[74:77], v[30:31], off offset:128 nt
	s_waitcnt lgkmcnt(0)
	global_load_dwordx4 v[70:73], v[30:31], off offset:160 nt
	v_lshl_add_u64 v[22:23], v[22:23], 0, v[106:107]
	v_lshl_add_u64 v[22:23], v[22:23], 0, v[174:175]
	v_add_co_u32_e32 v24, vcc, s41, v22
	v_add_u32_e32 v97, v201, v200
	s_nop 0
	v_addc_co_u32_e32 v25, vcc, 0, v23, vcc
	v_add_u32_e32 v102, v202, v200
	v_add_co_u32_e32 v22, vcc, s42, v22
	v_add_u32_e32 v26, 0x3400, v97
	v_add_u32_e32 v27, 0x3400, v102
	v_addc_co_u32_e32 v23, vcc, 0, v23, vcc
	global_load_dwordx4 v[56:59], v[24:25], off
	global_load_dwordx4 v[60:63], v[22:23], off
	s_waitcnt vmcnt(14)
	ds_write_b128 v206, v[6:9]
	ds_write_b128 v207, v[2:5]
	s_waitcnt vmcnt(13)
	ds_write_b128 v208, v[10:13] offset:128
	s_waitcnt vmcnt(12)
	ds_write2_b64 v26, v[14:15], v[16:17] offset1:1
	s_waitcnt vmcnt(11)
	ds_write2_b64 v27, v[18:19], v[20:21] offset1:1
	s_waitcnt lgkmcnt(0)
	s_barrier
	ds_read_b128 v[2:5], v209
	ds_read_b128 v[34:37], v209 offset:32
	s_waitcnt vmcnt(10) lgkmcnt(1)
	v_mfma_f32_32x32x16_bf16 v[2:17], v[2:5], v[82:85], 0
	ds_read_b128 v[18:21], v209 offset:6656
	ds_read_b128 v[38:41], v209 offset:6688
	s_waitcnt lgkmcnt(1)
	v_mfma_f32_32x32x16_bf16 v[18:33], v[18:21], v[82:85], 0
	s_waitcnt vmcnt(9)
	v_mfma_f32_32x32x16_bf16 v[2:17], v[34:37], v[78:81], v[2:17]
	s_waitcnt lgkmcnt(0)
	v_mfma_f32_32x32x16_bf16 v[18:33], v[38:41], v[78:81], v[18:33]
	ds_read_b128 v[34:37], v209 offset:64
	ds_read_b128 v[38:41], v209 offset:96
	s_waitcnt vmcnt(7) lgkmcnt(1)
	v_mfma_f32_32x32x16_bf16 v[2:17], v[34:37], v[66:69], v[2:17]
	ds_read_b128 v[34:37], v209 offset:6720
	ds_read_b128 v[90:93], v209 offset:6752
	s_waitcnt lgkmcnt(1)
	v_mfma_f32_32x32x16_bf16 v[18:33], v[34:37], v[66:69], v[18:33]
	s_waitcnt vmcnt(4)
	v_mfma_f32_32x32x16_bf16 v[2:17], v[38:41], v[86:89], v[2:17]
	ds_read_b128 v[34:37], v209 offset:128
	ds_read_b128 v[38:41], v209 offset:160
	s_waitcnt lgkmcnt(2)
	v_mfma_f32_32x32x16_bf16 v[18:33], v[90:93], v[86:89], v[18:33]
	s_waitcnt vmcnt(3) lgkmcnt(1)
	v_mfma_f32_32x32x16_bf16 v[2:17], v[34:37], v[74:77], v[2:17]
	ds_read_b128 v[34:37], v209 offset:6784
	ds_read_b128 v[90:93], v209 offset:6816
	s_waitcnt lgkmcnt(1)
	v_mfma_f32_32x32x16_bf16 v[18:33], v[34:37], v[74:77], v[18:33]
	v_and_b32_e32 v35, 64, v210
	v_xor_b32_e32 v34, 32, v210
	v_add_u32_e32 v35, 64, v35
	v_cmp_lt_i32_e32 vcc, v34, v35
	s_nop 1
	v_cndmask_b32_e32 v34, v210, v34, vcc
	s_waitcnt vmcnt(2)
	v_mfma_f32_32x32x16_bf16 v[2:17], v[38:41], v[70:73], v[2:17]
	v_lshlrev_b32_e32 v96, 2, v34
	s_waitcnt lgkmcnt(0)
	v_mfma_f32_32x32x16_bf16 v[18:33], v[90:93], v[70:73], v[18:33]
	s_nop 8
	v_max3_f32 v34, v2, v3, v4
	v_max3_f32 v34, v34, v5, v6
	v_max3_f32 v34, v34, v7, v8
	v_max3_f32 v34, v34, v9, v10
	v_max3_f32 v34, v34, v11, v12
	v_max3_f32 v34, v34, v13, v14
	v_max3_f32 v34, v34, v15, v16
	v_max3_f32 v34, v34, v17, v18
	v_max3_f32 v34, v34, v19, v20
	v_max3_f32 v34, v34, v21, v22
	v_max3_f32 v34, v34, v23, v24
	v_max3_f32 v34, v34, v25, v26
	v_max3_f32 v34, v34, v27, v28
	v_max3_f32 v34, v34, v29, v30
	v_max3_f32 v34, v34, v31, v32
	v_max_f32_e32 v34, v34, v33
	ds_bpermute_b32 v35, v96, v34
	v_add_u32_e32 v104, 0x4000, v212
	s_waitcnt lgkmcnt(0)
	v_max_f32_e32 v35, v35, v35
	v_max_f32_e32 v94, v34, v35
	v_sub_f32_e32 v2, v2, v94
	v_sub_f32_e32 v18, v18, v94
	v_sub_f32_e32 v3, v3, v94
	v_sub_f32_e32 v19, v19, v94
	v_exp_f32_e32 v65, v2
	v_exp_f32_e32 v90, v18
	v_sub_f32_e32 v36, v6, v94
	v_exp_f32_e32 v2, v3
	v_exp_f32_e32 v6, v19
	v_sub_f32_e32 v37, v7, v94
	v_add_f32_e32 v7, v90, v65
	v_mov_b32_e32 v3, v1
	v_sub_f32_e32 v34, v4, v94
	v_sub_f32_e32 v20, v20, v94
	v_sub_f32_e32 v35, v5, v94
	v_pk_add_f32 v[4:5], v[6:7], v[2:3]
	v_sub_f32_e32 v21, v21, v94
	v_pk_add_f32 v[4:5], v[4:5], v[4:5] op_sel_hi:[0,1]
	v_exp_f32_e32 v3, v34
	v_exp_f32_e32 v7, v20
	v_sub_f32_e32 v38, v8, v94
	v_exp_f32_e32 v4, v35
	v_exp_f32_e32 v8, v21
	v_sub_f32_e32 v39, v9, v94
	v_add_f32_e32 v9, v7, v3
	v_sub_f32_e32 v22, v22, v94
	v_sub_f32_e32 v40, v10, v94
	v_sub_f32_e32 v41, v11, v94
	v_pk_add_f32 v[10:11], v[8:9], v[4:5]
	v_sub_f32_e32 v23, v23, v94
	v_pk_add_f32 v[10:11], v[10:11], v[10:11] op_sel_hi:[0,1]
	v_exp_f32_e32 v5, v36
	v_exp_f32_e32 v9, v22
	v_sub_f32_e32 v34, v12, v94
	v_exp_f32_e32 v10, v37
	v_exp_f32_e32 v12, v23
	v_sub_f32_e32 v35, v13, v94
	v_add_f32_e32 v13, v9, v5
	v_sub_f32_e32 v24, v24, v94
	v_pk_add_f32 v[18:19], v[12:13], v[10:11]
	v_sub_f32_e32 v25, v25, v94
	v_pk_add_f32 v[18:19], v[18:19], v[18:19] op_sel_hi:[0,1]
	v_exp_f32_e32 v11, v38
	v_exp_f32_e32 v13, v24
	v_exp_f32_e32 v18, v39
	v_exp_f32_e32 v20, v25
	v_sub_f32_e32 v26, v26, v94
	v_add_f32_e32 v21, v13, v11
	v_sub_f32_e32 v27, v27, v94
	v_pk_add_f32 v[22:23], v[20:21], v[18:19]
	v_exp_f32_e32 v19, v40
	v_pk_add_f32 v[22:23], v[22:23], v[22:23] op_sel_hi:[0,1]
	v_exp_f32_e32 v21, v26
	v_sub_f32_e32 v36, v14, v94
	v_exp_f32_e32 v22, v41
	v_exp_f32_e32 v14, v27
	v_sub_f32_e32 v37, v15, v94
	v_add_f32_e32 v15, v21, v19
	v_sub_f32_e32 v28, v28, v94
	v_pk_add_f32 v[24:25], v[14:15], v[22:23]
	v_sub_f32_e32 v29, v29, v94
	v_pk_add_f32 v[24:25], v[24:25], v[24:25] op_sel_hi:[0,1]
	v_exp_f32_e32 v15, v34
	v_exp_f32_e32 v23, v28
	v_exp_f32_e32 v24, v35
	v_exp_f32_e32 v26, v29
	v_sub_f32_e32 v30, v30, v94
	v_add_f32_e32 v27, v23, v15
	v_sub_f32_e32 v31, v31, v94
	v_pk_add_f32 v[28:29], v[26:27], v[24:25]
	v_exp_f32_e32 v25, v36
	v_pk_add_f32 v[28:29], v[28:29], v[28:29] op_sel_hi:[0,1]
	v_exp_f32_e32 v27, v30
	v_sub_f32_e32 v34, v16, v94
	v_exp_f32_e32 v28, v37
	v_exp_f32_e32 v16, v31
	v_sub_f32_e32 v35, v17, v94
	v_add_f32_e32 v17, v27, v25
	v_sub_f32_e32 v32, v32, v94
	v_pk_add_f32 v[30:31], v[16:17], v[28:29]
	v_sub_f32_e32 v33, v33, v94
	v_pk_add_f32 v[42:43], v[30:31], v[30:31] op_sel_hi:[0,1]
	v_cvt_pk_bf16_f32 v2, v65, v2
	v_add_u32_e32 v65, 0x3000, v212
	v_exp_f32_e32 v95, v34
	v_exp_f32_e32 v103, v32
	v_exp_f32_e32 v42, v35
	v_exp_f32_e32 v64, v33
	v_cvt_pk_bf16_f32 v3, v3, v4
	v_cvt_pk_bf16_f32 v4, v5, v10
	v_cvt_pk_bf16_f32 v5, v11, v18
	v_cvt_pk_bf16_f32 v34, v19, v22
	v_cvt_pk_bf16_f32 v35, v15, v24
	v_cvt_pk_bf16_f32 v36, v25, v28
	v_cvt_pk_bf16_f32 v37, v95, v42
	v_cvt_pk_bf16_f32 v38, v90, v6
	v_cvt_pk_bf16_f32 v39, v7, v8
	v_cvt_pk_bf16_f32 v40, v9, v12
	v_cvt_pk_bf16_f32 v41, v13, v20
	v_cvt_pk_bf16_f32 v90, v21, v14
	v_cvt_pk_bf16_f32 v91, v23, v26
	v_cvt_pk_bf16_f32 v92, v27, v16
	v_cvt_pk_bf16_f32 v93, v103, v64
	ds_read2_b64 v[6:9], v65 offset0:128 offset1:130
	ds_read2_b64 v[98:101], v65 offset0:132 offset1:134
	s_waitcnt lgkmcnt(1)
	v_mfma_f32_32x32x16_bf16 v[18:33], v[6:9], v[2:5], 0
	ds_read2_b64 v[6:9], v104 offset0:160 offset1:162
	s_waitcnt lgkmcnt(1)
	v_mfma_f32_32x32x16_bf16 v[18:33], v[98:101], v[34:37], v[18:33]
	ds_read2_b64 v[98:101], v104 offset0:164 offset1:166
	s_waitcnt lgkmcnt(1)
	v_mfma_f32_32x32x16_bf16 v[2:17], v[6:9], v[2:5], 0
	s_waitcnt lgkmcnt(0)
	v_mfma_f32_32x32x16_bf16 v[2:17], v[98:101], v[34:37], v[2:17]
	ds_read2_b64 v[34:37], v65 offset0:136 offset1:138
	ds_read2_b64 v[98:101], v104 offset0:172 offset1:174
	s_waitcnt lgkmcnt(1)
	v_mfma_f32_32x32x16_bf16 v[18:33], v[34:37], v[38:41], v[18:33]
	ds_read2_b64 v[34:37], v104 offset0:168 offset1:170
	s_waitcnt lgkmcnt(0)
	v_mfma_f32_32x32x16_bf16 v[2:17], v[34:37], v[38:41], v[2:17]
	ds_read2_b64 v[34:37], v65 offset0:140 offset1:142
	v_add_f32_e32 v65, v103, v95
	v_add_f32_e64 v38, v64, v42
	v_add_f32_e64 v39, v65, v43
	v_add_u32_e32 v43, 0x8a00, v97
	s_waitcnt vmcnt(0)
	ds_write_b128 v206, v[60:63] offset:22016
	ds_write_b128 v207, v[56:59] offset:22016
	ds_write_b128 v208, v[52:55] offset:22144
	ds_write2_b64 v43, v[48:49], v[50:51] offset1:1
	v_add_u32_e32 v43, 0x8a00, v102
	ds_write2_b64 v43, v[44:45], v[46:47] offset1:1
	s_waitcnt lgkmcnt(0)
	s_barrier
	ds_read_b128 v[102:105], v209 offset:22016
	ds_read_b128 v[108:111], v209 offset:22048
	v_mfma_f32_32x32x16_bf16 v[18:33], v[34:37], v[90:93], v[18:33]
	v_add_f32_e64 v34, v38, v39
	v_add_f32_e64 v35, v39, v38
	v_mov_b32_e32 v35, v94
	v_add_f32_e64 v94, v34, 0
	v_add_f32_e64 v95, v35, 0
	v_xor_b32_e32 v34, 0x80000000, v95
	v_mov_b32_e32 v35, v34
	v_mov_b32_e32 v36, v34
	v_mov_b32_e32 v37, v34
	v_mov_b32_e32 v38, v34
	v_mov_b32_e32 v39, v34
	v_mov_b32_e32 v40, v34
	v_mov_b32_e32 v41, v34
	v_mov_b32_e32 v42, v34
	v_mov_b32_e32 v43, v34
	v_mov_b32_e32 v44, v34
	v_mov_b32_e32 v45, v34
	v_mov_b32_e32 v46, v34
	v_mov_b32_e32 v47, v34
	v_mov_b32_e32 v48, v34
	v_mov_b32_e32 v49, v34
	v_mfma_f32_32x32x16_bf16 v[2:17], v[98:101], v[90:93], v[2:17]
	s_waitcnt lgkmcnt(1)
	v_mfma_f32_32x32x16_bf16 v[50:65], v[102:105], v[82:85], v[34:49]
	ds_read_b128 v[102:105], v209 offset:28672
	ds_read_b128 v[112:115], v209 offset:28704
	s_waitcnt lgkmcnt(1)
	v_mfma_f32_32x32x16_bf16 v[34:49], v[102:105], v[82:85], v[34:49]
	v_mfma_f32_32x32x16_bf16 v[50:65], v[108:111], v[78:81], v[50:65]
	s_waitcnt lgkmcnt(0)
	v_mfma_f32_32x32x16_bf16 v[34:49], v[112:115], v[78:81], v[34:49]
	ds_read_b128 v[78:81], v209 offset:22080
	ds_read_b128 v[82:85], v209 offset:22112
	s_waitcnt lgkmcnt(1)
	v_mfma_f32_32x32x16_bf16 v[50:65], v[78:81], v[66:69], v[50:65]
	ds_read_b128 v[78:81], v209 offset:28736
	ds_read_b128 v[102:105], v209 offset:28768
	s_waitcnt lgkmcnt(1)
	v_mfma_f32_32x32x16_bf16 v[34:49], v[78:81], v[66:69], v[34:49]
	ds_read_b128 v[66:69], v209 offset:22144
	ds_read_b128 v[78:81], v209 offset:22176
	v_mfma_f32_32x32x16_bf16 v[50:65], v[82:85], v[86:89], v[50:65]
	s_waitcnt lgkmcnt(2)
	v_mfma_f32_32x32x16_bf16 v[34:49], v[102:105], v[86:89], v[34:49]
	s_waitcnt lgkmcnt(1)
	v_mfma_f32_32x32x16_bf16 v[50:65], v[66:69], v[74:77], v[50:65]
	ds_read_b128 v[66:69], v209 offset:28800
	ds_read_b128 v[82:85], v209 offset:28832
	s_waitcnt lgkmcnt(1)
	v_mfma_f32_32x32x16_bf16 v[34:49], v[66:69], v[74:77], v[34:49]
	v_mfma_f32_32x32x16_bf16 v[50:65], v[78:81], v[70:73], v[50:65]
	s_waitcnt lgkmcnt(0)
	v_mfma_f32_32x32x16_bf16 v[34:49], v[82:85], v[70:73], v[34:49]
	s_nop 9
	v_max3_f32 v66, v50, v51, v52
	v_max3_f32 v66, v66, v53, v54
	v_max3_f32 v66, v66, v55, v56
	v_max3_f32 v66, v66, v57, v58
	v_max3_f32 v66, v66, v59, v60
	v_max3_f32 v66, v66, v61, v62
	v_max3_f32 v66, v66, v63, v64
	v_max3_f32 v66, v66, v65, v34
	v_max3_f32 v66, v66, v35, v36
	v_max3_f32 v66, v66, v37, v38
	v_max3_f32 v66, v66, v39, v40
	v_max3_f32 v66, v66, v41, v42
	v_max3_f32 v66, v66, v43, v44
	v_max3_f32 v66, v66, v45, v46
	v_max3_f32 v66, v66, v47, v48
	v_max_f32_e32 v66, v66, v49
	ds_bpermute_b32 v67, v96, v66
	s_waitcnt lgkmcnt(0)
	v_max_f32_e32 v67, v67, v67
	v_max_f32_e32 v66, v66, v67
	v_cmp_lt_f32_e32 vcc, s45, v66
	s_cbranch_vccz .LBB0_934
	v_max_f32_e32 v66, v66, v66
	v_max_f32_e32 v66, 0, v66
	v_exp_f32_e64 v68, -v66
	v_pk_add_f32 v[50:51], v[50:51], v[66:67] op_sel_hi:[1,0] neg_lo:[0,1] neg_hi:[0,1]
	v_pk_add_f32 v[34:35], v[34:35], v[66:67] op_sel_hi:[1,0] neg_lo:[0,1] neg_hi:[0,1]
	v_pk_add_f32 v[52:53], v[52:53], v[66:67] op_sel_hi:[1,0] neg_lo:[0,1] neg_hi:[0,1]
	v_pk_add_f32 v[36:37], v[36:37], v[66:67] op_sel_hi:[1,0] neg_lo:[0,1] neg_hi:[0,1]
	v_pk_add_f32 v[54:55], v[54:55], v[66:67] op_sel_hi:[1,0] neg_lo:[0,1] neg_hi:[0,1]
	v_pk_add_f32 v[38:39], v[38:39], v[66:67] op_sel_hi:[1,0] neg_lo:[0,1] neg_hi:[0,1]
	v_pk_add_f32 v[56:57], v[56:57], v[66:67] op_sel_hi:[1,0] neg_lo:[0,1] neg_hi:[0,1]
	v_pk_add_f32 v[40:41], v[40:41], v[66:67] op_sel_hi:[1,0] neg_lo:[0,1] neg_hi:[0,1]
	v_pk_add_f32 v[58:59], v[58:59], v[66:67] op_sel_hi:[1,0] neg_lo:[0,1] neg_hi:[0,1]
	v_pk_add_f32 v[42:43], v[42:43], v[66:67] op_sel_hi:[1,0] neg_lo:[0,1] neg_hi:[0,1]
	v_pk_add_f32 v[60:61], v[60:61], v[66:67] op_sel_hi:[1,0] neg_lo:[0,1] neg_hi:[0,1]
	v_pk_add_f32 v[44:45], v[44:45], v[66:67] op_sel_hi:[1,0] neg_lo:[0,1] neg_hi:[0,1]
	v_pk_add_f32 v[62:63], v[62:63], v[66:67] op_sel_hi:[1,0] neg_lo:[0,1] neg_hi:[0,1]
	v_pk_add_f32 v[46:47], v[46:47], v[66:67] op_sel_hi:[1,0] neg_lo:[0,1] neg_hi:[0,1]
	v_pk_add_f32 v[64:65], v[64:65], v[66:67] op_sel_hi:[1,0] neg_lo:[0,1] neg_hi:[0,1]
	v_pk_add_f32 v[48:49], v[48:49], v[66:67] op_sel_hi:[1,0] neg_lo:[0,1] neg_hi:[0,1]
	v_mov_b32_e32 v67, v66
	v_pk_add_f32 v[66:67], v[94:95], v[66:67]
	v_pk_mul_f32 v[32:33], v[32:33], v[68:69] op_sel_hi:[1,0]
	v_pk_mul_f32 v[30:31], v[30:31], v[68:69] op_sel_hi:[1,0]
	v_pk_mul_f32 v[28:29], v[28:29], v[68:69] op_sel_hi:[1,0]
	v_pk_mul_f32 v[26:27], v[26:27], v[68:69] op_sel_hi:[1,0]
	v_pk_mul_f32 v[24:25], v[24:25], v[68:69] op_sel_hi:[1,0]
	v_pk_mul_f32 v[22:23], v[22:23], v[68:69] op_sel_hi:[1,0]
	v_pk_mul_f32 v[20:21], v[20:21], v[68:69] op_sel_hi:[1,0]
	v_pk_mul_f32 v[18:19], v[18:19], v[68:69] op_sel_hi:[1,0]
	v_pk_mul_f32 v[16:17], v[16:17], v[68:69] op_sel_hi:[1,0]
	v_pk_mul_f32 v[14:15], v[14:15], v[68:69] op_sel_hi:[1,0]
	v_pk_mul_f32 v[12:13], v[12:13], v[68:69] op_sel_hi:[1,0]
	v_pk_mul_f32 v[10:11], v[10:11], v[68:69] op_sel_hi:[1,0]
	v_pk_mul_f32 v[8:9], v[8:9], v[68:69] op_sel_hi:[1,0]
	v_pk_mul_f32 v[6:7], v[6:7], v[68:69] op_sel_hi:[1,0]
	v_pk_mul_f32 v[4:5], v[4:5], v[68:69] op_sel_hi:[1,0]
	v_pk_mul_f32 v[2:3], v[2:3], v[68:69] op_sel_hi:[1,0]
	v_mul_f32_e32 v94, v94, v68
	v_mov_b32_e32 v95, v67

.LBB0_942:
	ds_read_b128 v[76:79], v209 offset:22016
	ds_read_b128 v[188:191], v209 offset:22048
	v_add_f32_e32 v75, v249, v246
	v_add_f32_e32 v75, 0, v75
	v_add_f32_e32 v80, v243, v240
	s_waitcnt lgkmcnt(1)
	v_mfma_f32_32x32x16_bf16 v[50:65], v[76:79], v[102:105], v[34:49]
	ds_read_b128 v[76:79], v209 offset:28672
	ds_read_b128 v[192:195], v209 offset:28704
	v_add_f32_e32 v72, v239, v72
	v_add_f32_e32 v73, v74, v73
	v_add_f32_e32 v66, v69, v66
	v_add_f32_e32 v67, v70, v67
	v_add_f32_e32 v0, v230, v0
	s_waitcnt lgkmcnt(1)
	v_mfma_f32_32x32x16_bf16 v[34:49], v[76:79], v[102:105], v[34:49]
	v_mfma_f32_32x32x16_bf16 v[50:65], v[188:191], v[98:101], v[50:65]
	ds_read_b128 v[76:79], v209 offset:22080
	ds_read_b128 v[188:191], v209 offset:22112
	s_waitcnt lgkmcnt(2)
	v_mfma_f32_32x32x16_bf16 v[34:49], v[192:195], v[98:101], v[34:49]
	s_waitcnt lgkmcnt(1)
	v_mfma_f32_32x32x16_bf16 v[50:65], v[76:79], v[82:85], v[50:65]
	ds_read_b128 v[76:79], v209 offset:28736
	ds_read_b128 v[192:195], v209 offset:28768
	s_waitcnt lgkmcnt(1)
	v_mfma_f32_32x32x16_bf16 v[34:49], v[76:79], v[82:85], v[34:49]
	v_add_f32_e32 v76, v250, v247
	v_add_f32_e32 v75, v76, v75
	v_add_f32_e32 v76, v251, v248
	v_add_f32_e32 v75, v76, v75
	ds_read_b128 v[76:79], v209 offset:22144
	v_add_f32_e32 v75, v80, v75
	v_add_f32_e32 v80, v244, v241
	s_waitcnt lgkmcnt(1)
	v_mfma_f32_32x32x16_bf16 v[34:49], v[192:195], v[86:89], v[34:49]
	v_add_f32_e32 v75, v80, v75
	v_add_f32_e32 v80, v245, v242
	v_add_f32_e32 v75, v80, v75
	v_mfma_f32_32x32x16_bf16 v[50:65], v[188:191], v[86:89], v[50:65]
	ds_read_b128 v[188:191], v209 offset:28800
	ds_read_b128 v[192:195], v209 offset:22176
	s_waitcnt lgkmcnt(1)
	v_mfma_f32_32x32x16_bf16 v[34:49], v[188:191], v[90:93], v[34:49]
	v_add_f32_e32 v189, v71, v68
	v_mfma_f32_32x32x16_bf16 v[50:65], v[76:79], v[90:93], v[50:65]
	v_add_f32_e32 v76, v238, v237
	ds_read_b128 v[238:241], v209 offset:28832
	v_add_f32_e32 v75, v76, v75
	v_add_f32_e32 v72, v72, v75
	v_add_f32_e32 v72, v73, v72
	v_add_f32_e32 v66, v66, v72
	v_add_f32_e32 v188, v67, v66
	s_nop 2
	v_mov_b64_e32 v[80:81], v[48:49]
	v_mov_b64_e32 v[78:79], v[46:47]
	v_mov_b64_e32 v[76:77], v[44:45]
	v_mov_b64_e32 v[74:75], v[42:43]
	v_mov_b64_e32 v[72:73], v[40:41]
	v_mov_b64_e32 v[70:71], v[38:39]
	v_mov_b64_e32 v[68:69], v[36:37]
	v_mov_b64_e32 v[66:67], v[34:35]
	s_waitcnt lgkmcnt(1)
	v_mfma_f32_32x32x16_bf16 v[50:65], v[192:195], v[94:97], v[50:65]
	v_add_f32_e32 v34, v189, v188
	v_add_f32_e32 v35, v234, v231
	v_add_f32_e32 v34, v35, v34
	v_add_f32_e32 v35, v235, v232
	v_add_f32_e32 v34, v35, v34
	v_add_f32_e32 v35, v236, v233
	v_add_f32_e32 v34, v35, v34
	s_waitcnt lgkmcnt(0)
	v_mfma_f32_32x32x16_bf16 v[66:81], v[238:241], v[94:97], v[66:81]
	s_nop 2
	v_add_f32_e32 v0, v0, v34
	v_add_f32_e32 v0, v175, v0
	v_max3_f32 v36, v50, v51, v52
	v_max3_f32 v36, v36, v53, v54
	v_max3_f32 v36, v36, v55, v56
	v_max3_f32 v36, v36, v57, v58
	v_max3_f32 v36, v36, v59, v60
	v_max3_f32 v36, v36, v61, v62
	v_max3_f32 v36, v36, v63, v64
	s_nop 1
	v_max3_f32 v36, v36, v65, v66
	v_max3_f32 v36, v36, v67, v68
	v_max3_f32 v36, v36, v69, v70
	v_max3_f32 v36, v36, v71, v72
	v_max3_f32 v36, v36, v73, v74
	v_max3_f32 v36, v36, v75, v76
	v_max3_f32 v36, v36, v77, v78
	v_max3_f32 v36, v36, v79, v80
	v_max_f32_e32 v36, v36, v81
	ds_bpermute_b32 v37, v149, v36
	s_waitcnt lgkmcnt(0)
	v_max_f32_e32 v34, v37, v37
	v_max_f32_e32 v34, v36, v34
	v_cmp_lt_f32_e32 vcc, s45, v34
	s_cbranch_vccz .LBB0_958
	v_max_f32_e32 v34, v34, v34
	v_max_f32_e32 v36, 0, v34
	v_exp_f32_e64 v38, -v36
	v_add_f32_e32 v173, v173, v36
	v_xor_b32_e32 v34, 0x80000000, v173
	v_pk_add_f32 v[50:51], v[50:51], v[36:37] op_sel_hi:[1,0] neg_lo:[0,1] neg_hi:[0,1]
	v_pk_add_f32 v[66:67], v[66:67], v[36:37] op_sel_hi:[1,0] neg_lo:[0,1] neg_hi:[0,1]
	v_pk_add_f32 v[52:53], v[52:53], v[36:37] op_sel_hi:[1,0] neg_lo:[0,1] neg_hi:[0,1]
	v_pk_add_f32 v[68:69], v[68:69], v[36:37] op_sel_hi:[1,0] neg_lo:[0,1] neg_hi:[0,1]
	v_pk_add_f32 v[54:55], v[54:55], v[36:37] op_sel_hi:[1,0] neg_lo:[0,1] neg_hi:[0,1]
	v_pk_add_f32 v[70:71], v[70:71], v[36:37] op_sel_hi:[1,0] neg_lo:[0,1] neg_hi:[0,1]
	v_pk_add_f32 v[56:57], v[56:57], v[36:37] op_sel_hi:[1,0] neg_lo:[0,1] neg_hi:[0,1]
	v_pk_add_f32 v[72:73], v[72:73], v[36:37] op_sel_hi:[1,0] neg_lo:[0,1] neg_hi:[0,1]
	v_pk_add_f32 v[58:59], v[58:59], v[36:37] op_sel_hi:[1,0] neg_lo:[0,1] neg_hi:[0,1]
	v_pk_add_f32 v[74:75], v[74:75], v[36:37] op_sel_hi:[1,0] neg_lo:[0,1] neg_hi:[0,1]
	v_pk_add_f32 v[60:61], v[60:61], v[36:37] op_sel_hi:[1,0] neg_lo:[0,1] neg_hi:[0,1]
	v_pk_add_f32 v[76:77], v[76:77], v[36:37] op_sel_hi:[1,0] neg_lo:[0,1] neg_hi:[0,1]
	v_pk_add_f32 v[62:63], v[62:63], v[36:37] op_sel_hi:[1,0] neg_lo:[0,1] neg_hi:[0,1]
	v_pk_add_f32 v[78:79], v[78:79], v[36:37] op_sel_hi:[1,0] neg_lo:[0,1] neg_hi:[0,1]
	v_pk_add_f32 v[64:65], v[64:65], v[36:37] op_sel_hi:[1,0] neg_lo:[0,1] neg_hi:[0,1]
	v_pk_add_f32 v[80:81], v[80:81], v[36:37] op_sel_hi:[1,0] neg_lo:[0,1] neg_hi:[0,1]
	v_pk_mul_f32 v[32:33], v[32:33], v[38:39] op_sel_hi:[1,0]
	v_pk_mul_f32 v[30:31], v[30:31], v[38:39] op_sel_hi:[1,0]
	v_pk_mul_f32 v[28:29], v[28:29], v[38:39] op_sel_hi:[1,0]
	v_pk_mul_f32 v[26:27], v[26:27], v[38:39] op_sel_hi:[1,0]
	v_pk_mul_f32 v[24:25], v[24:25], v[38:39] op_sel_hi:[1,0]
	v_pk_mul_f32 v[22:23], v[22:23], v[38:39] op_sel_hi:[1,0]
	v_pk_mul_f32 v[20:21], v[20:21], v[38:39] op_sel_hi:[1,0]
	v_pk_mul_f32 v[18:19], v[18:19], v[38:39] op_sel_hi:[1,0]
	v_pk_mul_f32 v[16:17], v[16:17], v[38:39] op_sel_hi:[1,0]
	v_pk_mul_f32 v[14:15], v[14:15], v[38:39] op_sel_hi:[1,0]
	v_pk_mul_f32 v[12:13], v[12:13], v[38:39] op_sel_hi:[1,0]
	v_pk_mul_f32 v[10:11], v[10:11], v[38:39] op_sel_hi:[1,0]
	v_pk_mul_f32 v[8:9], v[8:9], v[38:39] op_sel_hi:[1,0]
	v_pk_mul_f32 v[6:7], v[6:7], v[38:39] op_sel_hi:[1,0]
	v_pk_mul_f32 v[4:5], v[4:5], v[38:39] op_sel_hi:[1,0]
	v_pk_mul_f32 v[2:3], v[2:3], v[38:39] op_sel_hi:[1,0]
	v_mul_f32_e32 v0, v0, v38
	v_mov_b32_e32 v35, v34
	v_mov_b32_e32 v36, v34
	v_mov_b32_e32 v37, v34
	v_mov_b32_e32 v38, v34
	v_mov_b32_e32 v39, v34
	v_mov_b32_e32 v40, v34
	v_mov_b32_e32 v41, v34
	v_mov_b32_e32 v42, v34
	v_mov_b32_e32 v43, v34
	v_mov_b32_e32 v44, v34
	v_mov_b32_e32 v45, v34
	v_mov_b32_e32 v46, v34
	v_mov_b32_e32 v47, v34
	v_mov_b32_e32 v48, v34
	v_mov_b32_e32 v49, v34

.LBB0_947:
	ds_read_b128 v[66:69], v209
	ds_read_b128 v[216:219], v209 offset:32
	ds_read_b128 v[220:223], v209 offset:6656
	ds_read_b128 v[224:227], v209 offset:6688
	s_cmp_eq_u32 s10, 0
	s_cselect_b64 s[2:3], -1, 0
	s_waitcnt lgkmcnt(3)
	v_mfma_f32_32x32x16_bf16 v[50:65], v[66:69], v[102:105], v[34:49]
	s_cmp_lg_u32 s10, 0
	s_waitcnt lgkmcnt(1)
	v_mfma_f32_32x32x16_bf16 v[66:81], v[220:223], v[102:105], v[34:49]
	v_mfma_f32_32x32x16_bf16 v[50:65], v[216:219], v[98:101], v[50:65]
	ds_read_b128 v[216:219], v209 offset:64
	ds_read_b128 v[220:223], v209 offset:96
	s_waitcnt lgkmcnt(2)
	v_mfma_f32_32x32x16_bf16 v[66:81], v[224:227], v[98:101], v[66:81]
	s_waitcnt lgkmcnt(1)
	v_mfma_f32_32x32x16_bf16 v[50:65], v[216:219], v[82:85], v[50:65]
	ds_read_b128 v[216:219], v209 offset:6720
	ds_read_b128 v[224:227], v209 offset:6752
	s_waitcnt lgkmcnt(1)
	v_mfma_f32_32x32x16_bf16 v[66:81], v[216:219], v[82:85], v[66:81]
	v_mfma_f32_32x32x16_bf16 v[50:65], v[220:223], v[86:89], v[50:65]
	ds_read_b128 v[216:219], v209 offset:128
	ds_read_b128 v[220:223], v209 offset:160
	s_waitcnt lgkmcnt(2)
	v_mfma_f32_32x32x16_bf16 v[66:81], v[224:227], v[86:89], v[66:81]
	s_waitcnt lgkmcnt(1)
	v_mfma_f32_32x32x16_bf16 v[50:65], v[216:219], v[90:93], v[50:65]
	ds_read_b128 v[216:219], v209 offset:6784
	ds_read_b128 v[224:227], v209 offset:6816
	s_waitcnt lgkmcnt(1)
	v_mfma_f32_32x32x16_bf16 v[66:81], v[216:219], v[90:93], v[66:81]
	s_waitcnt lgkmcnt(0)
	v_mfma_f32_32x32x16_bf16 v[66:81], v[224:227], v[94:97], v[66:81]
	v_mfma_f32_32x32x16_bf16 v[50:65], v[220:223], v[94:97], v[50:65]
	s_nop 10
	v_max3_f32 v0, v50, v51, v52
	v_max3_f32 v0, v0, v53, v54
	v_max3_f32 v0, v0, v55, v56
	v_max3_f32 v0, v0, v57, v58
	v_max3_f32 v0, v0, v59, v60
	v_max3_f32 v0, v0, v61, v62
	v_max3_f32 v0, v0, v63, v64
	v_max3_f32 v0, v0, v65, v66
	v_max3_f32 v0, v0, v67, v68
	v_max3_f32 v0, v0, v69, v70
	v_max3_f32 v0, v0, v71, v72
	v_max3_f32 v0, v0, v73, v74
	v_max3_f32 v0, v0, v75, v76
	v_max3_f32 v0, v0, v77, v78
	v_max3_f32 v0, v0, v79, v80
	v_max_f32_e32 v0, v0, v81
	ds_bpermute_b32 v177, v149, v0
	s_waitcnt lgkmcnt(0)
	v_max_f32_e32 v177, v177, v177
	v_max_f32_e32 v177, v0, v177
	s_cbranch_scc0 .LBB0_954
	v_cmp_lt_f32_e32 vcc, s45, v177
	s_mov_b64 s[62:63], 0
	s_mov_b64 s[34:35], 0
	s_cbranch_vccz .LBB0_950
	v_max_f32_e32 v0, v177, v177
	v_max_f32_e32 v0, 0, v0
	s_mov_b64 s[34:35], -1
